# static s_setprio 1 at kernel entry for waves 4-7 (younger half), timing-only
# baseline (speedup 1.0000x reference)
_Z14fwd_megakernel6Params:
	s_load_dwordx2 s[70:71], s[0:1], 0x128
	s_load_dword s33, s[0:1], 0x130
	s_mov_b64 s[66:67], s[0:1]
	s_add_u32 s0, s66, 0x128
	v_and_b32_e32 v178, 0x3ff, v0
	s_mov_b32 s68, s2
	s_addc_u32 s1, s67, 0
	v_readfirstlane_b32 s32, v0
	s_nop 3
	s_bfe_u32 s32, s32, 0x40006
	s_cmp_ge_u32 s32, 4
	s_cbranch_scc0 .Lprio_done
	s_setprio 1
.Lprio_done:
	v_cmp_gt_u32_e32 vcc, 4, v178
	s_and_saveexec_b64 s[2:3], vcc
	v_lshl_add_u32 v1, v178, 2, 0
	v_add_u32_e32 v1, 0x27fc0, v1
	v_mov_b32_e32 v2, 0
	ds_write_b32 v1, v2
	s_or_b64 exec, exec, s[2:3]
	s_cmp_lg_u32 s68, 0
	s_mov_b32 s2, 0
	s_cbranch_scc1 .LBB0_10
	s_mov_b64 s[4:5], s[66:67]
	s_load_dwordx2 s[4:5], s[4:5], 0x120
	v_sub_u32_e32 v1, 0xd7f, v178
	v_lshrrev_b32_e32 v2, 9, v1
	v_add_u32_e32 v1, 2, v2
	v_add_u32_e32 v179, 0x200, v178
	s_waitcnt lgkmcnt(0)
	s_add_u32 s6, s4, 0x31c0000
	v_and_b32_e32 v3, 14, v1
	s_addc_u32 s7, s5, 0
	v_mov_b32_e32 v1, v2
	s_mov_b64 s[8:9], 0
	s_mov_b32 s3, 1
	v_mov_b32_e32 v5, 0
	s_mov_b32 s10, s2
	v_mov_b64_e32 v[6:7], v[178:179]
	s_branch .LBB0_5
